# GEMM K-loop heads aligned to 64 bytes (on top of aligned hand-written loop heads)
# speedup vs baseline: 1.0021x; 1.0005x over previous
; template <class Epi, class Sched, bool ALIGN_EPI = false, bool SP2 = false>
; __device__ __forceinline__ void gemm_phase(PG8_LAS unsigned char* lds, const Gemm g, const Sched& S, const Epi& E) {
;     ...
;     for (;;) {
;         const bool has_next = S.next(ui + 1, nxt);
;         const char* nA = has_next ? (const char*)g.A + (size_t)nxt.pm * tstep : cA; const char* nB = has_next ? (const char*)g.Bt + (size_t)nxt.pn * tstep : cB;
;         for (int t = 0; t < nt; t += 2) {
;             const bool last = (t == nt - 2);
;             const char* a1 = cA + (size_t)(t + 1) * kstep;
;             const char* a2 = last ? nA : cA + (size_t)(t + 2) * kstep; const char* b2 = last ? nB : cB + (size_t)(t + 2) * kstep;
;             const char* a3 = a2 + kstep; const char* b3 = b2 + kstep;
;     ...
; #pragma unroll
;         for (int a = 0; a < 2; ++a)
; #pragma unroll
;             for (int b = 0; b < 2; ++b)
; #pragma unroll
;                 for (int m = 0; m < 4; ++m)
; #pragma unroll
;                     for (int n = 0; n < 2; ++n) acc[a][b][m][n] = (f32x4){0.f, 0.f, 0.f, 0.f};
;         cur = nxt; cA = nA; cB = nB; ++ui;
.LBB0_289:
	v_mov_b32_e32 v127, 0
	s_andn2_b64 vcc, exec, s[38:39]
	v_mov_b32_e32 v126, v127
	v_mov_b32_e32 v125, v127
	v_mov_b32_e32 v124, v127
	v_mov_b32_e32 v119, v127
	v_mov_b32_e32 v118, v127
	v_mov_b32_e32 v117, v127
	v_mov_b32_e32 v116, v127
	v_mov_b32_e32 v111, v127
	v_mov_b32_e32 v110, v127
	v_mov_b32_e32 v109, v127
	v_mov_b32_e32 v108, v127
	v_mov_b32_e32 v103, v127
	v_mov_b32_e32 v102, v127
	v_mov_b32_e32 v101, v127
	v_mov_b32_e32 v100, v127
	v_mov_b32_e32 v95, v127
	v_mov_b32_e32 v94, v127
	v_mov_b32_e32 v93, v127
	v_mov_b32_e32 v92, v127
	v_mov_b32_e32 v87, v127
	v_mov_b32_e32 v86, v127
	v_mov_b32_e32 v85, v127
	v_mov_b32_e32 v84, v127
	v_mov_b32_e32 v79, v127
	v_mov_b32_e32 v78, v127
	v_mov_b32_e32 v77, v127
	v_mov_b32_e32 v76, v127
	v_mov_b32_e32 v71, v127
	v_mov_b32_e32 v70, v127
	v_mov_b32_e32 v69, v127
	v_mov_b32_e32 v68, v127
	v_mov_b32_e32 v123, v127
	v_mov_b32_e32 v122, v127
	v_mov_b32_e32 v121, v127
	v_mov_b32_e32 v120, v127
	v_mov_b32_e32 v115, v127
	v_mov_b32_e32 v114, v127
	v_mov_b32_e32 v113, v127
	v_mov_b32_e32 v112, v127
	v_mov_b32_e32 v107, v127
	v_mov_b32_e32 v106, v127
	v_mov_b32_e32 v105, v127
	v_mov_b32_e32 v104, v127
	v_mov_b32_e32 v99, v127
	v_mov_b32_e32 v98, v127
	v_mov_b32_e32 v97, v127
	v_mov_b32_e32 v96, v127
	v_mov_b32_e32 v91, v127
	v_mov_b32_e32 v90, v127
	v_mov_b32_e32 v89, v127
	v_mov_b32_e32 v88, v127
	v_mov_b32_e32 v83, v127
	v_mov_b32_e32 v82, v127
	v_mov_b32_e32 v81, v127
	v_mov_b32_e32 v80, v127
	v_mov_b32_e32 v75, v127
	v_mov_b32_e32 v74, v127
	v_mov_b32_e32 v73, v127
	v_mov_b32_e32 v72, v127
	v_mov_b32_e32 v67, v127
	v_mov_b32_e32 v66, v127
	v_mov_b32_e32 v65, v127
	v_mov_b32_e32 v64, v127
	v_mov_b32_e32 v63, v127
	v_mov_b32_e32 v62, v127
	v_mov_b32_e32 v61, v127
	v_mov_b32_e32 v60, v127
	v_mov_b32_e32 v55, v127
	v_mov_b32_e32 v54, v127
	v_mov_b32_e32 v53, v127
	v_mov_b32_e32 v52, v127
	v_mov_b32_e32 v47, v127
	v_mov_b32_e32 v46, v127
	v_mov_b32_e32 v45, v127
	v_mov_b32_e32 v44, v127
	v_mov_b32_e32 v39, v127
	v_mov_b32_e32 v38, v127
	v_mov_b32_e32 v37, v127
	v_mov_b32_e32 v36, v127
	v_mov_b32_e32 v31, v127
	v_mov_b32_e32 v30, v127
	v_mov_b32_e32 v29, v127
	v_mov_b32_e32 v28, v127
	v_mov_b32_e32 v23, v127
	v_mov_b32_e32 v22, v127
	v_mov_b32_e32 v21, v127
	v_mov_b32_e32 v20, v127
	v_mov_b32_e32 v15, v127
	v_mov_b32_e32 v14, v127
	v_mov_b32_e32 v13, v127
	v_mov_b32_e32 v12, v127
	v_mov_b32_e32 v7, v127
	v_mov_b32_e32 v6, v127
	v_mov_b32_e32 v5, v127
	v_mov_b32_e32 v4, v127
	v_mov_b32_e32 v59, v127
	v_mov_b32_e32 v58, v127
	v_mov_b32_e32 v57, v127
	v_mov_b32_e32 v56, v127
	v_mov_b32_e32 v51, v127
	v_mov_b32_e32 v50, v127
	v_mov_b32_e32 v49, v127
	v_mov_b32_e32 v48, v127
	v_mov_b32_e32 v43, v127
	v_mov_b32_e32 v42, v127
	v_mov_b32_e32 v41, v127
	v_mov_b32_e32 v40, v127
	v_mov_b32_e32 v35, v127
	v_mov_b32_e32 v34, v127
	v_mov_b32_e32 v33, v127
	v_mov_b32_e32 v32, v127
	v_mov_b32_e32 v27, v127
	v_mov_b32_e32 v26, v127
	v_mov_b32_e32 v25, v127
	v_mov_b32_e32 v24, v127
	v_mov_b32_e32 v19, v127
	v_mov_b32_e32 v18, v127
	v_mov_b32_e32 v17, v127
	v_mov_b32_e32 v16, v127
	v_mov_b32_e32 v11, v127
	v_mov_b32_e32 v10, v127
	v_mov_b32_e32 v9, v127
	v_mov_b32_e32 v8, v127
	v_mov_b32_e32 v3, v127
	v_mov_b32_e32 v2, v127
	v_mov_b32_e32 v1, v127
	v_mov_b32_e32 v0, v127
	s_cbranch_vccnz .LBB0_292
	s_add_u32 s71, s44, 0x100
	s_addc_u32 s72, s45, 0
	s_add_u32 s44, s46, 0x80
	v_mov_b32_e32 v0, 0
	s_addc_u32 s45, s47, 0
	s_mov_b32 s46, 0
	v_mov_b32_e32 v1, v0
	v_mov_b32_e32 v2, v0
	v_mov_b32_e32 v3, v0
	v_mov_b32_e32 v8, v0
	v_mov_b32_e32 v9, v0
	v_mov_b32_e32 v10, v0
	v_mov_b32_e32 v11, v0
	v_mov_b32_e32 v16, v0
	v_mov_b32_e32 v17, v0
	v_mov_b32_e32 v18, v0
	v_mov_b32_e32 v19, v0
	v_mov_b32_e32 v24, v0
	v_mov_b32_e32 v25, v0
	v_mov_b32_e32 v26, v0
	v_mov_b32_e32 v27, v0
	v_mov_b32_e32 v32, v0
	v_mov_b32_e32 v33, v0
	v_mov_b32_e32 v34, v0
	v_mov_b32_e32 v35, v0
	v_mov_b32_e32 v40, v0
	v_mov_b32_e32 v41, v0
	v_mov_b32_e32 v42, v0
	v_mov_b32_e32 v43, v0
	v_mov_b32_e32 v48, v0
	v_mov_b32_e32 v49, v0
	v_mov_b32_e32 v50, v0
	v_mov_b32_e32 v51, v0
	v_mov_b32_e32 v56, v0
	v_mov_b32_e32 v57, v0
	v_mov_b32_e32 v58, v0
	v_mov_b32_e32 v59, v0
	v_mov_b32_e32 v4, v0
	v_mov_b32_e32 v5, v0
	v_mov_b32_e32 v6, v0
	v_mov_b32_e32 v7, v0
	v_mov_b32_e32 v12, v0
	v_mov_b32_e32 v13, v0
	v_mov_b32_e32 v14, v0
	v_mov_b32_e32 v15, v0
	v_mov_b32_e32 v20, v0
	v_mov_b32_e32 v21, v0
	v_mov_b32_e32 v22, v0
	v_mov_b32_e32 v23, v0
	v_mov_b32_e32 v28, v0
	v_mov_b32_e32 v29, v0
	v_mov_b32_e32 v30, v0
	v_mov_b32_e32 v31, v0
	v_mov_b32_e32 v36, v0
	v_mov_b32_e32 v37, v0
	v_mov_b32_e32 v38, v0
	v_mov_b32_e32 v39, v0
	v_mov_b32_e32 v44, v0
	v_mov_b32_e32 v45, v0
	v_mov_b32_e32 v46, v0
	v_mov_b32_e32 v47, v0
	v_mov_b32_e32 v52, v0
	v_mov_b32_e32 v53, v0
	v_mov_b32_e32 v54, v0
	v_mov_b32_e32 v55, v0
	v_mov_b32_e32 v60, v0
	v_mov_b32_e32 v61, v0
	v_mov_b32_e32 v62, v0
	v_mov_b32_e32 v63, v0
	v_mov_b32_e32 v64, v0
	v_mov_b32_e32 v65, v0
	v_mov_b32_e32 v66, v0
	v_mov_b32_e32 v67, v0
	v_mov_b32_e32 v72, v0
	v_mov_b32_e32 v73, v0
	v_mov_b32_e32 v74, v0
	v_mov_b32_e32 v75, v0
	v_mov_b32_e32 v80, v0
	v_mov_b32_e32 v81, v0
	v_mov_b32_e32 v82, v0
	v_mov_b32_e32 v83, v0
	v_mov_b32_e32 v88, v0
	v_mov_b32_e32 v89, v0
	v_mov_b32_e32 v90, v0
	v_mov_b32_e32 v91, v0
	v_mov_b32_e32 v96, v0
	v_mov_b32_e32 v97, v0
	v_mov_b32_e32 v98, v0
	v_mov_b32_e32 v99, v0
	v_mov_b32_e32 v104, v0
	v_mov_b32_e32 v105, v0
	v_mov_b32_e32 v106, v0
	v_mov_b32_e32 v107, v0
	v_mov_b32_e32 v112, v0
	v_mov_b32_e32 v113, v0
	v_mov_b32_e32 v114, v0
	v_mov_b32_e32 v115, v0
	v_mov_b32_e32 v120, v0
	v_mov_b32_e32 v121, v0
	v_mov_b32_e32 v122, v0
	v_mov_b32_e32 v123, v0
	v_mov_b32_e32 v68, v0
	v_mov_b32_e32 v69, v0
	v_mov_b32_e32 v70, v0
	v_mov_b32_e32 v71, v0
	v_mov_b32_e32 v76, v0
	v_mov_b32_e32 v77, v0
	v_mov_b32_e32 v78, v0
	v_mov_b32_e32 v79, v0
	v_mov_b32_e32 v84, v0
	v_mov_b32_e32 v85, v0
	v_mov_b32_e32 v86, v0
	v_mov_b32_e32 v87, v0
	v_mov_b32_e32 v92, v0
	v_mov_b32_e32 v93, v0
	v_mov_b32_e32 v94, v0
	v_mov_b32_e32 v95, v0
	v_mov_b32_e32 v100, v0
	v_mov_b32_e32 v101, v0
	v_mov_b32_e32 v102, v0
	v_mov_b32_e32 v103, v0
	v_mov_b32_e32 v108, v0
	v_mov_b32_e32 v109, v0
	v_mov_b32_e32 v110, v0
	v_mov_b32_e32 v111, v0
	v_mov_b32_e32 v116, v0
	v_mov_b32_e32 v117, v0
	v_mov_b32_e32 v118, v0
	v_mov_b32_e32 v119, v0
	v_mov_b32_e32 v124, v0
	v_mov_b32_e32 v125, v0
	v_mov_b32_e32 v126, v0
	v_mov_b32_e32 v127, v0
	.p2align 6

; template <class Epi, class Sched, bool ALIGN_EPI = false, bool SP2 = false>
; __device__ __forceinline__ void gemm_phase(PG8_LAS unsigned char* lds, const Gemm g, const Sched& S, const Epi& E) {
;     ...
;     for (;;) {
;         const bool has_next = S.next(ui + 1, nxt);
;         const char* nA = has_next ? (const char*)g.A + (size_t)nxt.pm * tstep : cA; const char* nB = has_next ? (const char*)g.Bt + (size_t)nxt.pn * tstep : cB;
;         for (int t = 0; t < nt; t += 2) {
;             const bool last = (t == nt - 2);
;             const char* a1 = cA + (size_t)(t + 1) * kstep;
;             const char* a2 = last ? nA : cA + (size_t)(t + 2) * kstep; const char* b2 = last ? nB : cB + (size_t)(t + 2) * kstep;
;             const char* a3 = a2 + kstep; const char* b3 = b2 + kstep;
.LBB0_386:
	s_add_u32 s72, s36, 0x100
	s_addc_u32 s73, s37, 0
	s_add_u32 s46, s38, 0x80
	s_addc_u32 s47, s39, 0
	s_mov_b32 s48, 0
	.p2align 6

; template <class Epi, class Sched, bool ALIGN_EPI = false, bool SP2 = false>
; __device__ __forceinline__ void gemm_phase(PG8_LAS unsigned char* lds, const Gemm g, const Sched& S, const Epi& E) {
;     ...
;     for (;;) {
;         const bool has_next = S.next(ui + 1, nxt);
;         const char* nA = has_next ? (const char*)g.A + (size_t)nxt.pm * tstep : cA; const char* nB = has_next ? (const char*)g.Bt + (size_t)nxt.pn * tstep : cB;
;         for (int t = 0; t < nt; t += 2) {
;             const bool last = (t == nt - 2);
;             const char* a1 = cA + (size_t)(t + 1) * kstep;
;             const char* a2 = last ? nA : cA + (size_t)(t + 2) * kstep; const char* b2 = last ? nB : cB + (size_t)(t + 2) * kstep;
;             const char* a3 = a2 + kstep; const char* b3 = b2 + kstep;
;     ...
; #pragma unroll
;         for (int a = 0; a < 2; ++a)
; #pragma unroll
;             for (int b = 0; b < 2; ++b)
; #pragma unroll
;                 for (int m = 0; m < 4; ++m)
; #pragma unroll
;                     for (int n = 0; n < 2; ++n) acc[a][b][m][n] = (f32x4){0.f, 0.f, 0.f, 0.f};
;         cur = nxt; cA = nA; cB = nB; ++ui;
.LBB0_504:
	v_mov_b32_e32 v127, 0
	s_andn2_b64 vcc, exec, s[36:37]
	v_mov_b32_e32 v126, 0
	v_mov_b32_e32 v125, 0
	v_mov_b32_e32 v124, 0
	v_mov_b32_e32 v123, 0
	v_mov_b32_e32 v122, 0
	v_mov_b32_e32 v121, 0
	v_mov_b32_e32 v120, 0
	v_mov_b32_e32 v101, 0
	v_mov_b32_e32 v100, 0
	v_mov_b32_e32 v103, 0
	v_mov_b32_e32 v102, 0
	v_mov_b32_e32 v109, 0
	v_mov_b32_e32 v108, 0
	v_mov_b32_e32 v111, 0
	v_mov_b32_e32 v110, 0
	v_mov_b32_e32 v85, 0
	v_mov_b32_e32 v84, 0
	v_mov_b32_e32 v87, 0
	v_mov_b32_e32 v86, 0
	v_mov_b32_e32 v93, 0
	v_mov_b32_e32 v92, 0
	v_mov_b32_e32 v95, 0
	v_mov_b32_e32 v94, 0
	v_mov_b32_e32 v73, 0
	v_mov_b32_e32 v72, 0
	v_mov_b32_e32 v75, 0
	v_mov_b32_e32 v74, 0
	v_mov_b32_e32 v77, 0
	v_mov_b32_e32 v76, 0
	v_mov_b32_e32 v79, 0
	v_mov_b32_e32 v78, 0
	v_mov_b32_e32 v157, 0
	v_mov_b32_e32 v156, 0
	v_mov_b32_e32 v159, 0
	v_mov_b32_e32 v158, 0
	v_mov_b32_e32 v161, 0
	v_mov_b32_e32 v160, 0
	v_mov_b32_e32 v163, 0
	v_mov_b32_e32 v162, 0
	v_mov_b32_e32 v113, 0
	v_mov_b32_e32 v112, 0
	v_mov_b32_e32 v115, 0
	v_mov_b32_e32 v114, 0
	v_mov_b32_e32 v117, 0
	v_mov_b32_e32 v116, 0
	v_mov_b32_e32 v119, 0
	v_mov_b32_e32 v118, 0
	v_mov_b32_e32 v97, 0
	v_mov_b32_e32 v96, 0
	v_mov_b32_e32 v99, 0
	v_mov_b32_e32 v98, 0
	v_mov_b32_e32 v105, 0
	v_mov_b32_e32 v104, 0
	v_mov_b32_e32 v107, 0
	v_mov_b32_e32 v106, 0
	v_mov_b32_e32 v71, 0
	v_mov_b32_e32 v70, 0
	v_mov_b32_e32 v69, 0
	v_mov_b32_e32 v68, 0
	v_mov_b32_e32 v67, 0
	v_mov_b32_e32 v66, 0
	v_mov_b32_e32 v65, 0
	v_mov_b32_e32 v64, 0
	v_mov_b32_e32 v63, 0
	v_mov_b32_e32 v62, 0
	v_mov_b32_e32 v61, 0
	v_mov_b32_e32 v60, 0
	v_mov_b32_e32 v59, 0
	v_mov_b32_e32 v58, 0
	v_mov_b32_e32 v57, 0
	v_mov_b32_e32 v56, 0
	v_mov_b32_e32 v37, 0
	v_mov_b32_e32 v36, 0
	v_mov_b32_e32 v39, 0
	v_mov_b32_e32 v38, 0
	v_mov_b32_e32 v45, 0
	v_mov_b32_e32 v44, 0
	v_mov_b32_e32 v47, 0
	v_mov_b32_e32 v46, 0
	v_mov_b32_e32 v21, 0
	v_mov_b32_e32 v20, 0
	v_mov_b32_e32 v23, 0
	v_mov_b32_e32 v22, 0
	v_mov_b32_e32 v29, 0
	v_mov_b32_e32 v28, 0
	v_mov_b32_e32 v31, 0
	v_mov_b32_e32 v30, 0
	v_mov_b32_e32 v9, 0
	v_mov_b32_e32 v8, 0
	v_mov_b32_e32 v11, 0
	v_mov_b32_e32 v10, 0
	v_mov_b32_e32 v13, 0
	v_mov_b32_e32 v12, 0
	v_mov_b32_e32 v15, 0
	v_mov_b32_e32 v14, 0
	v_mov_b32_e32 v81, 0
	v_mov_b32_e32 v80, 0
	v_mov_b32_e32 v83, 0
	v_mov_b32_e32 v82, 0
	v_mov_b32_e32 v89, 0
	v_mov_b32_e32 v88, 0
	v_mov_b32_e32 v91, 0
	v_mov_b32_e32 v90, 0
	v_mov_b32_e32 v49, 0
	v_mov_b32_e32 v48, 0
	v_mov_b32_e32 v51, 0
	v_mov_b32_e32 v50, 0
	v_mov_b32_e32 v53, 0
	v_mov_b32_e32 v52, 0
	v_mov_b32_e32 v55, 0
	v_mov_b32_e32 v54, 0
	v_mov_b32_e32 v33, 0
	v_mov_b32_e32 v32, 0
	v_mov_b32_e32 v35, 0
	v_mov_b32_e32 v34, 0
	v_mov_b32_e32 v41, 0
	v_mov_b32_e32 v40, 0
	v_mov_b32_e32 v43, 0
	v_mov_b32_e32 v42, 0
	v_mov_b32_e32 v7, 0
	v_mov_b32_e32 v6, 0
	v_mov_b32_e32 v5, 0
	v_mov_b32_e32 v4, 0
	v_mov_b32_e32 v3, 0
	v_mov_b32_e32 v2, 0
	v_mov_b32_e32 v1, 0
	v_mov_b32_e32 v0, 0
	s_cbranch_vccnz .LBB0_508
	s_add_u32 s77, s50, 0x100
	s_addc_u32 s78, s51, 0
	s_add_u32 s50, s52, 0x80
	v_mov_b32_e32 v0, 0
	s_addc_u32 s51, s53, 0
	s_mov_b32 s52, 0
	v_mov_b32_e32 v1, v0
	v_mov_b32_e32 v2, v0
	v_mov_b32_e32 v3, v0
	v_mov_b32_e32 v4, v0
	v_mov_b32_e32 v5, v0
	v_mov_b32_e32 v6, v0
	v_mov_b32_e32 v7, v0
	v_mov_b32_e32 v8, v0
	v_mov_b32_e32 v9, v0
	v_mov_b32_e32 v10, v0
	v_mov_b32_e32 v11, v0
	v_mov_b32_e32 v12, v0
	v_mov_b32_e32 v13, v0
	v_mov_b32_e32 v14, v0
	v_mov_b32_e32 v15, v0
	v_mov_b32_e32 v20, v0
	v_mov_b32_e32 v21, v0
	v_mov_b32_e32 v22, v0
	v_mov_b32_e32 v23, v0
	v_mov_b32_e32 v28, v0
	v_mov_b32_e32 v29, v0
	v_mov_b32_e32 v30, v0
	v_mov_b32_e32 v31, v0
	v_mov_b32_e32 v36, v0
	v_mov_b32_e32 v37, v0
	v_mov_b32_e32 v38, v0
	v_mov_b32_e32 v39, v0
	v_mov_b32_e32 v44, v0
	v_mov_b32_e32 v45, v0
	v_mov_b32_e32 v46, v0
	v_mov_b32_e32 v47, v0
	v_mov_b32_e32 v16, v0
	v_mov_b32_e32 v17, v0
	v_mov_b32_e32 v18, v0
	v_mov_b32_e32 v19, v0
	v_mov_b32_e32 v24, v0
	v_mov_b32_e32 v25, v0
	v_mov_b32_e32 v26, v0
	v_mov_b32_e32 v27, v0
	v_mov_b32_e32 v32, v0
	v_mov_b32_e32 v33, v0
	v_mov_b32_e32 v34, v0
	v_mov_b32_e32 v35, v0
	v_mov_b32_e32 v40, v0
	v_mov_b32_e32 v41, v0
	v_mov_b32_e32 v42, v0
	v_mov_b32_e32 v43, v0
	v_mov_b32_e32 v48, v0
	v_mov_b32_e32 v49, v0
	v_mov_b32_e32 v50, v0
	v_mov_b32_e32 v51, v0
	v_mov_b32_e32 v52, v0
	v_mov_b32_e32 v53, v0
	v_mov_b32_e32 v54, v0
	v_mov_b32_e32 v55, v0
	v_mov_b32_e32 v56, v0
	v_mov_b32_e32 v57, v0
	v_mov_b32_e32 v58, v0
	v_mov_b32_e32 v59, v0
	v_mov_b32_e32 v60, v0
	v_mov_b32_e32 v61, v0
	v_mov_b32_e32 v62, v0
	v_mov_b32_e32 v63, v0
	v_mov_b32_e32 v64, v0
	v_mov_b32_e32 v65, v0
	v_mov_b32_e32 v66, v0
	v_mov_b32_e32 v67, v0
	v_mov_b32_e32 v68, v0
	v_mov_b32_e32 v69, v0
	v_mov_b32_e32 v70, v0
	v_mov_b32_e32 v71, v0
	v_mov_b32_e32 v72, v0
	v_mov_b32_e32 v73, v0
	v_mov_b32_e32 v74, v0
	v_mov_b32_e32 v75, v0
	v_mov_b32_e32 v76, v0
	v_mov_b32_e32 v77, v0
	v_mov_b32_e32 v78, v0
	v_mov_b32_e32 v79, v0
	v_mov_b32_e32 v84, v0
	v_mov_b32_e32 v85, v0
	v_mov_b32_e32 v86, v0
	v_mov_b32_e32 v87, v0
	v_mov_b32_e32 v92, v0
	v_mov_b32_e32 v93, v0
	v_mov_b32_e32 v94, v0
	v_mov_b32_e32 v95, v0
	v_mov_b32_e32 v100, v0
	v_mov_b32_e32 v101, v0
	v_mov_b32_e32 v102, v0
	v_mov_b32_e32 v103, v0
	v_mov_b32_e32 v108, v0
	v_mov_b32_e32 v109, v0
	v_mov_b32_e32 v110, v0
	v_mov_b32_e32 v111, v0
	v_mov_b32_e32 v80, v0
	v_mov_b32_e32 v81, v0
	v_mov_b32_e32 v82, v0
	v_mov_b32_e32 v83, v0
	v_mov_b32_e32 v88, v0
	v_mov_b32_e32 v89, v0
	v_mov_b32_e32 v90, v0
	v_mov_b32_e32 v91, v0
	v_mov_b32_e32 v96, v0
	v_mov_b32_e32 v97, v0
	v_mov_b32_e32 v98, v0
	v_mov_b32_e32 v99, v0
	v_mov_b32_e32 v104, v0
	v_mov_b32_e32 v105, v0
	v_mov_b32_e32 v106, v0
	v_mov_b32_e32 v107, v0
	v_mov_b32_e32 v112, v0
	v_mov_b32_e32 v113, v0
	v_mov_b32_e32 v114, v0
	v_mov_b32_e32 v115, v0
	v_mov_b32_e32 v116, v0
	v_mov_b32_e32 v117, v0
	v_mov_b32_e32 v118, v0
	v_mov_b32_e32 v119, v0
	v_mov_b32_e32 v120, v0
	v_mov_b32_e32 v121, v0
	v_mov_b32_e32 v122, v0
	v_mov_b32_e32 v123, v0
	v_mov_b32_e32 v124, v0
	v_mov_b32_e32 v125, v0
	v_mov_b32_e32 v126, v0
	v_mov_b32_e32 v127, v0
	.p2align 6

; template <class Epi, class Sched, bool ALIGN_EPI = false, bool SP2 = false>
; __device__ __forceinline__ void gemm_phase(PG8_LAS unsigned char* lds, const Gemm g, const Sched& S, const Epi& E) {
;     ...
;     for (;;) {
;         const bool has_next = S.next(ui + 1, nxt);
;         const char* nA = has_next ? (const char*)g.A + (size_t)nxt.pm * tstep : cA; const char* nB = has_next ? (const char*)g.Bt + (size_t)nxt.pn * tstep : cB;
;         for (int t = 0; t < nt; t += 2) {
;             const bool last = (t == nt - 2);
;             const char* a1 = cA + (size_t)(t + 1) * kstep;
;             const char* a2 = last ? nA : cA + (size_t)(t + 2) * kstep; const char* b2 = last ? nB : cB + (size_t)(t + 2) * kstep;
;             const char* a3 = a2 + kstep; const char* b3 = b2 + kstep;
;     ...
; #pragma unroll
;         for (int a = 0; a < 2; ++a)
; #pragma unroll
;             for (int b = 0; b < 2; ++b)
; #pragma unroll
;                 for (int m = 0; m < 4; ++m)
; #pragma unroll
;                     for (int n = 0; n < 2; ++n) acc[a][b][m][n] = (f32x4){0.f, 0.f, 0.f, 0.f};
;         cur = nxt; cA = nA; cB = nB; ++ui;
.LBB0_648:
	v_mov_b32_e32 v127, 0
	s_andn2_b64 vcc, exec, s[40:41]
	v_mov_b32_e32 v126, v127
	v_mov_b32_e32 v125, v127
	v_mov_b32_e32 v124, v127
	v_mov_b32_e32 v123, v127
	v_mov_b32_e32 v122, v127
	v_mov_b32_e32 v121, v127
	v_mov_b32_e32 v120, v127
	v_mov_b32_e32 v111, v127
	v_mov_b32_e32 v110, v127
	v_mov_b32_e32 v109, v127
	v_mov_b32_e32 v108, v127
	v_mov_b32_e32 v107, v127
	v_mov_b32_e32 v106, v127
	v_mov_b32_e32 v105, v127
	v_mov_b32_e32 v104, v127
	v_mov_b32_e32 v95, v127
	v_mov_b32_e32 v94, v127
	v_mov_b32_e32 v93, v127
	v_mov_b32_e32 v92, v127
	v_mov_b32_e32 v91, v127
	v_mov_b32_e32 v90, v127
	v_mov_b32_e32 v89, v127
	v_mov_b32_e32 v88, v127
	v_mov_b32_e32 v79, v127
	v_mov_b32_e32 v78, v127
	v_mov_b32_e32 v77, v127
	v_mov_b32_e32 v76, v127
	v_mov_b32_e32 v75, v127
	v_mov_b32_e32 v74, v127
	v_mov_b32_e32 v73, v127
	v_mov_b32_e32 v72, v127
	v_mov_b32_e32 v119, v127
	v_mov_b32_e32 v118, v127
	v_mov_b32_e32 v117, v127
	v_mov_b32_e32 v116, v127
	v_mov_b32_e32 v115, v127
	v_mov_b32_e32 v114, v127
	v_mov_b32_e32 v113, v127
	v_mov_b32_e32 v112, v127
	v_mov_b32_e32 v103, v127
	v_mov_b32_e32 v102, v127
	v_mov_b32_e32 v101, v127
	v_mov_b32_e32 v100, v127
	v_mov_b32_e32 v99, v127
	v_mov_b32_e32 v98, v127
	v_mov_b32_e32 v97, v127
	v_mov_b32_e32 v96, v127
	v_mov_b32_e32 v87, v127
	v_mov_b32_e32 v86, v127
	v_mov_b32_e32 v85, v127
	v_mov_b32_e32 v84, v127
	v_mov_b32_e32 v83, v127
	v_mov_b32_e32 v82, v127
	v_mov_b32_e32 v81, v127
	v_mov_b32_e32 v80, v127
	v_mov_b32_e32 v71, v127
	v_mov_b32_e32 v70, v127
	v_mov_b32_e32 v69, v127
	v_mov_b32_e32 v68, v127
	v_mov_b32_e32 v67, v127
	v_mov_b32_e32 v66, v127
	v_mov_b32_e32 v65, v127
	v_mov_b32_e32 v64, v127
	v_mov_b32_e32 v63, v127
	v_mov_b32_e32 v62, v127
	v_mov_b32_e32 v61, v127
	v_mov_b32_e32 v60, v127
	v_mov_b32_e32 v59, v127
	v_mov_b32_e32 v58, v127
	v_mov_b32_e32 v57, v127
	v_mov_b32_e32 v56, v127
	v_mov_b32_e32 v47, v127
	v_mov_b32_e32 v46, v127
	v_mov_b32_e32 v45, v127
	v_mov_b32_e32 v44, v127
	v_mov_b32_e32 v43, v127
	v_mov_b32_e32 v42, v127
	v_mov_b32_e32 v41, v127
	v_mov_b32_e32 v40, v127
	v_mov_b32_e32 v31, v127
	v_mov_b32_e32 v30, v127
	v_mov_b32_e32 v29, v127
	v_mov_b32_e32 v28, v127
	v_mov_b32_e32 v27, v127
	v_mov_b32_e32 v26, v127
	v_mov_b32_e32 v25, v127
	v_mov_b32_e32 v24, v127
	v_mov_b32_e32 v15, v127
	v_mov_b32_e32 v14, v127
	v_mov_b32_e32 v13, v127
	v_mov_b32_e32 v12, v127
	v_mov_b32_e32 v11, v127
	v_mov_b32_e32 v10, v127
	v_mov_b32_e32 v9, v127
	v_mov_b32_e32 v8, v127
	v_mov_b32_e32 v55, v127
	v_mov_b32_e32 v54, v127
	v_mov_b32_e32 v53, v127
	v_mov_b32_e32 v52, v127
	v_mov_b32_e32 v51, v127
	v_mov_b32_e32 v50, v127
	v_mov_b32_e32 v49, v127
	v_mov_b32_e32 v48, v127
	v_mov_b32_e32 v39, v127
	v_mov_b32_e32 v38, v127
	v_mov_b32_e32 v37, v127
	v_mov_b32_e32 v36, v127
	v_mov_b32_e32 v35, v127
	v_mov_b32_e32 v34, v127
	v_mov_b32_e32 v33, v127
	v_mov_b32_e32 v32, v127
	v_mov_b32_e32 v23, v127
	v_mov_b32_e32 v22, v127
	v_mov_b32_e32 v21, v127
	v_mov_b32_e32 v20, v127
	v_mov_b32_e32 v19, v127
	v_mov_b32_e32 v18, v127
	v_mov_b32_e32 v17, v127
	v_mov_b32_e32 v16, v127
	v_mov_b32_e32 v7, v127
	v_mov_b32_e32 v6, v127
	v_mov_b32_e32 v5, v127
	v_mov_b32_e32 v4, v127
	v_mov_b32_e32 v3, v127
	v_mov_b32_e32 v2, v127
	v_mov_b32_e32 v1, v127
	v_mov_b32_e32 v0, v127
	s_cbranch_vccnz .LBB0_651
	s_add_u32 s72, s48, 0x100
	s_addc_u32 s73, s49, 0
	s_add_u32 s48, s50, 0x80
	v_mov_b32_e32 v0, 0
	s_addc_u32 s49, s51, 0
	s_mov_b32 s50, 0
	v_mov_b32_e32 v1, v0
	v_mov_b32_e32 v2, v0
	v_mov_b32_e32 v3, v0
	v_mov_b32_e32 v4, v0
	v_mov_b32_e32 v5, v0
	v_mov_b32_e32 v6, v0
	v_mov_b32_e32 v7, v0
	v_mov_b32_e32 v16, v0
	v_mov_b32_e32 v17, v0
	v_mov_b32_e32 v18, v0
	v_mov_b32_e32 v19, v0
	v_mov_b32_e32 v20, v0
	v_mov_b32_e32 v21, v0
	v_mov_b32_e32 v22, v0
	v_mov_b32_e32 v23, v0
	v_mov_b32_e32 v32, v0
	v_mov_b32_e32 v33, v0
	v_mov_b32_e32 v34, v0
	v_mov_b32_e32 v35, v0
	v_mov_b32_e32 v36, v0
	v_mov_b32_e32 v37, v0
	v_mov_b32_e32 v38, v0
	v_mov_b32_e32 v39, v0
	v_mov_b32_e32 v48, v0
	v_mov_b32_e32 v49, v0
	v_mov_b32_e32 v50, v0
	v_mov_b32_e32 v51, v0
	v_mov_b32_e32 v52, v0
	v_mov_b32_e32 v53, v0
	v_mov_b32_e32 v54, v0
	v_mov_b32_e32 v55, v0
	v_mov_b32_e32 v8, v0
	v_mov_b32_e32 v9, v0
	v_mov_b32_e32 v10, v0
	v_mov_b32_e32 v11, v0
	v_mov_b32_e32 v12, v0
	v_mov_b32_e32 v13, v0
	v_mov_b32_e32 v14, v0
	v_mov_b32_e32 v15, v0
	v_mov_b32_e32 v24, v0
	v_mov_b32_e32 v25, v0
	v_mov_b32_e32 v26, v0
	v_mov_b32_e32 v27, v0
	v_mov_b32_e32 v28, v0
	v_mov_b32_e32 v29, v0
	v_mov_b32_e32 v30, v0
	v_mov_b32_e32 v31, v0
	v_mov_b32_e32 v40, v0
	v_mov_b32_e32 v41, v0
	v_mov_b32_e32 v42, v0
	v_mov_b32_e32 v43, v0
	v_mov_b32_e32 v44, v0
	v_mov_b32_e32 v45, v0
	v_mov_b32_e32 v46, v0
	v_mov_b32_e32 v47, v0
	v_mov_b32_e32 v56, v0
	v_mov_b32_e32 v57, v0
	v_mov_b32_e32 v58, v0
	v_mov_b32_e32 v59, v0
	v_mov_b32_e32 v60, v0
	v_mov_b32_e32 v61, v0
	v_mov_b32_e32 v62, v0
	v_mov_b32_e32 v63, v0
	v_mov_b32_e32 v64, v0
	v_mov_b32_e32 v65, v0
	v_mov_b32_e32 v66, v0
	v_mov_b32_e32 v67, v0
	v_mov_b32_e32 v68, v0
	v_mov_b32_e32 v69, v0
	v_mov_b32_e32 v70, v0
	v_mov_b32_e32 v71, v0
	v_mov_b32_e32 v80, v0
	v_mov_b32_e32 v81, v0
	v_mov_b32_e32 v82, v0
	v_mov_b32_e32 v83, v0
	v_mov_b32_e32 v84, v0
	v_mov_b32_e32 v85, v0
	v_mov_b32_e32 v86, v0
	v_mov_b32_e32 v87, v0
	v_mov_b32_e32 v96, v0
	v_mov_b32_e32 v97, v0
	v_mov_b32_e32 v98, v0
	v_mov_b32_e32 v99, v0
	v_mov_b32_e32 v100, v0
	v_mov_b32_e32 v101, v0
	v_mov_b32_e32 v102, v0
	v_mov_b32_e32 v103, v0
	v_mov_b32_e32 v112, v0
	v_mov_b32_e32 v113, v0
	v_mov_b32_e32 v114, v0
	v_mov_b32_e32 v115, v0
	v_mov_b32_e32 v116, v0
	v_mov_b32_e32 v117, v0
	v_mov_b32_e32 v118, v0
	v_mov_b32_e32 v119, v0
	v_mov_b32_e32 v72, v0
	v_mov_b32_e32 v73, v0
	v_mov_b32_e32 v74, v0
	v_mov_b32_e32 v75, v0
	v_mov_b32_e32 v76, v0
	v_mov_b32_e32 v77, v0
	v_mov_b32_e32 v78, v0
	v_mov_b32_e32 v79, v0
	v_mov_b32_e32 v88, v0
	v_mov_b32_e32 v89, v0
	v_mov_b32_e32 v90, v0
	v_mov_b32_e32 v91, v0
	v_mov_b32_e32 v92, v0
	v_mov_b32_e32 v93, v0
	v_mov_b32_e32 v94, v0
	v_mov_b32_e32 v95, v0
	v_mov_b32_e32 v104, v0
	v_mov_b32_e32 v105, v0
	v_mov_b32_e32 v106, v0
	v_mov_b32_e32 v107, v0
	v_mov_b32_e32 v108, v0
	v_mov_b32_e32 v109, v0
	v_mov_b32_e32 v110, v0
	v_mov_b32_e32 v111, v0
	v_mov_b32_e32 v120, v0
	v_mov_b32_e32 v121, v0
	v_mov_b32_e32 v122, v0
	v_mov_b32_e32 v123, v0
	v_mov_b32_e32 v124, v0
	v_mov_b32_e32 v125, v0
	v_mov_b32_e32 v126, v0
	v_mov_b32_e32 v127, v0
	.p2align 6

; template <class Epi, class Sched, bool ALIGN_EPI = false, bool SP2 = false>
; __device__ __forceinline__ void gemm_phase(PG8_LAS unsigned char* lds, const Gemm g, const Sched& S, const Epi& E) {
;     ...
;     for (;;) {
;         const bool has_next = S.next(ui + 1, nxt);
;         const char* nA = has_next ? (const char*)g.A + (size_t)nxt.pm * tstep : cA; const char* nB = has_next ? (const char*)g.Bt + (size_t)nxt.pn * tstep : cB;
;         for (int t = 0; t < nt; t += 2) {
;             const bool last = (t == nt - 2);
;             const char* a1 = cA + (size_t)(t + 1) * kstep;
;             const char* a2 = last ? nA : cA + (size_t)(t + 2) * kstep; const char* b2 = last ? nB : cB + (size_t)(t + 2) * kstep;
;             const char* a3 = a2 + kstep; const char* b3 = b2 + kstep;
;     ...
; #pragma unroll
;         for (int a = 0; a < 2; ++a)
; #pragma unroll
;             for (int b = 0; b < 2; ++b)
; #pragma unroll
;                 for (int m = 0; m < 4; ++m)
; #pragma unroll
;                     for (int n = 0; n < 2; ++n) acc[a][b][m][n] = (f32x4){0.f, 0.f, 0.f, 0.f};
;         cur = nxt; cA = nA; cB = nB; ++ui;
.LBB0_681:
	v_mov_b32_e32 v127, 0
	s_andn2_b64 vcc, exec, s[40:41]
	v_mov_b32_e32 v126, v127
	v_mov_b32_e32 v125, v127
	v_mov_b32_e32 v124, v127
	v_mov_b32_e32 v123, v127
	v_mov_b32_e32 v122, v127
	v_mov_b32_e32 v121, v127
	v_mov_b32_e32 v120, v127
	v_mov_b32_e32 v111, v127
	v_mov_b32_e32 v110, v127
	v_mov_b32_e32 v109, v127
	v_mov_b32_e32 v108, v127
	v_mov_b32_e32 v107, v127
	v_mov_b32_e32 v106, v127
	v_mov_b32_e32 v105, v127
	v_mov_b32_e32 v104, v127
	v_mov_b32_e32 v95, v127
	v_mov_b32_e32 v94, v127
	v_mov_b32_e32 v93, v127
	v_mov_b32_e32 v92, v127
	v_mov_b32_e32 v91, v127
	v_mov_b32_e32 v90, v127
	v_mov_b32_e32 v89, v127
	v_mov_b32_e32 v88, v127
	v_mov_b32_e32 v79, v127
	v_mov_b32_e32 v78, v127
	v_mov_b32_e32 v77, v127
	v_mov_b32_e32 v76, v127
	v_mov_b32_e32 v75, v127
	v_mov_b32_e32 v74, v127
	v_mov_b32_e32 v73, v127
	v_mov_b32_e32 v72, v127
	v_mov_b32_e32 v119, v127
	v_mov_b32_e32 v118, v127
	v_mov_b32_e32 v117, v127
	v_mov_b32_e32 v116, v127
	v_mov_b32_e32 v115, v127
	v_mov_b32_e32 v114, v127
	v_mov_b32_e32 v113, v127
	v_mov_b32_e32 v112, v127
	v_mov_b32_e32 v103, v127
	v_mov_b32_e32 v102, v127
	v_mov_b32_e32 v101, v127
	v_mov_b32_e32 v100, v127
	v_mov_b32_e32 v99, v127
	v_mov_b32_e32 v98, v127
	v_mov_b32_e32 v97, v127
	v_mov_b32_e32 v96, v127
	v_mov_b32_e32 v87, v127
	v_mov_b32_e32 v86, v127
	v_mov_b32_e32 v85, v127
	v_mov_b32_e32 v84, v127
	v_mov_b32_e32 v83, v127
	v_mov_b32_e32 v82, v127
	v_mov_b32_e32 v81, v127
	v_mov_b32_e32 v80, v127
	v_mov_b32_e32 v71, v127
	v_mov_b32_e32 v70, v127
	v_mov_b32_e32 v69, v127
	v_mov_b32_e32 v68, v127
	v_mov_b32_e32 v67, v127
	v_mov_b32_e32 v66, v127
	v_mov_b32_e32 v65, v127
	v_mov_b32_e32 v64, v127
	v_mov_b32_e32 v63, v127
	v_mov_b32_e32 v62, v127
	v_mov_b32_e32 v61, v127
	v_mov_b32_e32 v60, v127
	v_mov_b32_e32 v59, v127
	v_mov_b32_e32 v58, v127
	v_mov_b32_e32 v57, v127
	v_mov_b32_e32 v56, v127
	v_mov_b32_e32 v47, v127
	v_mov_b32_e32 v46, v127
	v_mov_b32_e32 v45, v127
	v_mov_b32_e32 v44, v127
	v_mov_b32_e32 v43, v127
	v_mov_b32_e32 v42, v127
	v_mov_b32_e32 v41, v127
	v_mov_b32_e32 v40, v127
	v_mov_b32_e32 v31, v127
	v_mov_b32_e32 v30, v127
	v_mov_b32_e32 v29, v127
	v_mov_b32_e32 v28, v127
	v_mov_b32_e32 v27, v127
	v_mov_b32_e32 v26, v127
	v_mov_b32_e32 v25, v127
	v_mov_b32_e32 v24, v127
	v_mov_b32_e32 v15, v127
	v_mov_b32_e32 v14, v127
	v_mov_b32_e32 v13, v127
	v_mov_b32_e32 v12, v127
	v_mov_b32_e32 v11, v127
	v_mov_b32_e32 v10, v127
	v_mov_b32_e32 v9, v127
	v_mov_b32_e32 v8, v127
	v_mov_b32_e32 v55, v127
	v_mov_b32_e32 v54, v127
	v_mov_b32_e32 v53, v127
	v_mov_b32_e32 v52, v127
	v_mov_b32_e32 v51, v127
	v_mov_b32_e32 v50, v127
	v_mov_b32_e32 v49, v127
	v_mov_b32_e32 v48, v127
	v_mov_b32_e32 v39, v127
	v_mov_b32_e32 v38, v127
	v_mov_b32_e32 v37, v127
	v_mov_b32_e32 v36, v127
	v_mov_b32_e32 v35, v127
	v_mov_b32_e32 v34, v127
	v_mov_b32_e32 v33, v127
	v_mov_b32_e32 v32, v127
	v_mov_b32_e32 v23, v127
	v_mov_b32_e32 v22, v127
	v_mov_b32_e32 v21, v127
	v_mov_b32_e32 v20, v127
	v_mov_b32_e32 v19, v127
	v_mov_b32_e32 v18, v127
	v_mov_b32_e32 v17, v127
	v_mov_b32_e32 v16, v127
	v_mov_b32_e32 v7, v127
	v_mov_b32_e32 v6, v127
	v_mov_b32_e32 v5, v127
	v_mov_b32_e32 v4, v127
	v_mov_b32_e32 v3, v127
	v_mov_b32_e32 v2, v127
	v_mov_b32_e32 v1, v127
	v_mov_b32_e32 v0, v127
	s_cbranch_vccnz .LBB0_684
	s_add_u32 s87, s56, 0x100
	s_addc_u32 s88, s57, 0
	s_add_u32 s56, s58, 0x80
	v_mov_b32_e32 v0, 0
	s_addc_u32 s57, s59, 0
	s_mov_b32 s58, 0
	v_mov_b32_e32 v1, v0
	v_mov_b32_e32 v2, v0
	v_mov_b32_e32 v3, v0
	v_mov_b32_e32 v4, v0
	v_mov_b32_e32 v5, v0
	v_mov_b32_e32 v6, v0
	v_mov_b32_e32 v7, v0
	v_mov_b32_e32 v16, v0
	v_mov_b32_e32 v17, v0
	v_mov_b32_e32 v18, v0
	v_mov_b32_e32 v19, v0
	v_mov_b32_e32 v20, v0
	v_mov_b32_e32 v21, v0
	v_mov_b32_e32 v22, v0
	v_mov_b32_e32 v23, v0
	v_mov_b32_e32 v32, v0
	v_mov_b32_e32 v33, v0
	v_mov_b32_e32 v34, v0
	v_mov_b32_e32 v35, v0
	v_mov_b32_e32 v36, v0
	v_mov_b32_e32 v37, v0
	v_mov_b32_e32 v38, v0
	v_mov_b32_e32 v39, v0
	v_mov_b32_e32 v48, v0
	v_mov_b32_e32 v49, v0
	v_mov_b32_e32 v50, v0
	v_mov_b32_e32 v51, v0
	v_mov_b32_e32 v52, v0
	v_mov_b32_e32 v53, v0
	v_mov_b32_e32 v54, v0
	v_mov_b32_e32 v55, v0
	v_mov_b32_e32 v8, v0
	v_mov_b32_e32 v9, v0
	v_mov_b32_e32 v10, v0
	v_mov_b32_e32 v11, v0
	v_mov_b32_e32 v12, v0
	v_mov_b32_e32 v13, v0
	v_mov_b32_e32 v14, v0
	v_mov_b32_e32 v15, v0
	v_mov_b32_e32 v24, v0
	v_mov_b32_e32 v25, v0
	v_mov_b32_e32 v26, v0
	v_mov_b32_e32 v27, v0
	v_mov_b32_e32 v28, v0
	v_mov_b32_e32 v29, v0
	v_mov_b32_e32 v30, v0
	v_mov_b32_e32 v31, v0
	v_mov_b32_e32 v40, v0
	v_mov_b32_e32 v41, v0
	v_mov_b32_e32 v42, v0
	v_mov_b32_e32 v43, v0
	v_mov_b32_e32 v44, v0
	v_mov_b32_e32 v45, v0
	v_mov_b32_e32 v46, v0
	v_mov_b32_e32 v47, v0
	v_mov_b32_e32 v56, v0
	v_mov_b32_e32 v57, v0
	v_mov_b32_e32 v58, v0
	v_mov_b32_e32 v59, v0
	v_mov_b32_e32 v60, v0
	v_mov_b32_e32 v61, v0
	v_mov_b32_e32 v62, v0
	v_mov_b32_e32 v63, v0
	v_mov_b32_e32 v64, v0
	v_mov_b32_e32 v65, v0
	v_mov_b32_e32 v66, v0
	v_mov_b32_e32 v67, v0
	v_mov_b32_e32 v68, v0
	v_mov_b32_e32 v69, v0
	v_mov_b32_e32 v70, v0
	v_mov_b32_e32 v71, v0
	v_mov_b32_e32 v80, v0
	v_mov_b32_e32 v81, v0
	v_mov_b32_e32 v82, v0
	v_mov_b32_e32 v83, v0
	v_mov_b32_e32 v84, v0
	v_mov_b32_e32 v85, v0
	v_mov_b32_e32 v86, v0
	v_mov_b32_e32 v87, v0
	v_mov_b32_e32 v96, v0
	v_mov_b32_e32 v97, v0
	v_mov_b32_e32 v98, v0
	v_mov_b32_e32 v99, v0
	v_mov_b32_e32 v100, v0
	v_mov_b32_e32 v101, v0
	v_mov_b32_e32 v102, v0
	v_mov_b32_e32 v103, v0
	v_mov_b32_e32 v112, v0
	v_mov_b32_e32 v113, v0
	v_mov_b32_e32 v114, v0
	v_mov_b32_e32 v115, v0
	v_mov_b32_e32 v116, v0
	v_mov_b32_e32 v117, v0
	v_mov_b32_e32 v118, v0
	v_mov_b32_e32 v119, v0
	v_mov_b32_e32 v72, v0
	v_mov_b32_e32 v73, v0
	v_mov_b32_e32 v74, v0
	v_mov_b32_e32 v75, v0
	v_mov_b32_e32 v76, v0
	v_mov_b32_e32 v77, v0
	v_mov_b32_e32 v78, v0
	v_mov_b32_e32 v79, v0
	v_mov_b32_e32 v88, v0
	v_mov_b32_e32 v89, v0
	v_mov_b32_e32 v90, v0
	v_mov_b32_e32 v91, v0
	v_mov_b32_e32 v92, v0
	v_mov_b32_e32 v93, v0
	v_mov_b32_e32 v94, v0
	v_mov_b32_e32 v95, v0
	v_mov_b32_e32 v104, v0
	v_mov_b32_e32 v105, v0
	v_mov_b32_e32 v106, v0
	v_mov_b32_e32 v107, v0
	v_mov_b32_e32 v108, v0
	v_mov_b32_e32 v109, v0
	v_mov_b32_e32 v110, v0
	v_mov_b32_e32 v111, v0
	v_mov_b32_e32 v120, v0
	v_mov_b32_e32 v121, v0
	v_mov_b32_e32 v122, v0
	v_mov_b32_e32 v123, v0
	v_mov_b32_e32 v124, v0
	v_mov_b32_e32 v125, v0
	v_mov_b32_e32 v126, v0
	v_mov_b32_e32 v127, v0
	.p2align 6

; template <class Epi, class Sched, bool ALIGN_EPI = false, bool SP2 = false>
; __device__ __forceinline__ void gemm_phase(PG8_LAS unsigned char* lds, const Gemm g, const Sched& S, const Epi& E) {
;     ...
;     for (;;) {
;         const bool has_next = S.next(ui + 1, nxt);
;         const char* nA = has_next ? (const char*)g.A + (size_t)nxt.pm * tstep : cA; const char* nB = has_next ? (const char*)g.Bt + (size_t)nxt.pn * tstep : cB;
;         for (int t = 0; t < nt; t += 2) {
;             const bool last = (t == nt - 2);
;             const char* a1 = cA + (size_t)(t + 1) * kstep;
;             const char* a2 = last ? nA : cA + (size_t)(t + 2) * kstep; const char* b2 = last ? nB : cB + (size_t)(t + 2) * kstep;
;             const char* a3 = a2 + kstep; const char* b3 = b2 + kstep;
;     ...
; #pragma unroll
;         for (int a = 0; a < 2; ++a)
; #pragma unroll
;             for (int b = 0; b < 2; ++b)
; #pragma unroll
;                 for (int m = 0; m < 4; ++m)
; #pragma unroll
;                     for (int n = 0; n < 2; ++n) acc[a][b][m][n] = (f32x4){0.f, 0.f, 0.f, 0.f};
;         cur = nxt; cA = nA; cB = nB; ++ui;
.LBB0_710:
	v_mov_b32_e32 v127, 0
	s_andn2_b64 vcc, exec, s[8:9]
	v_mov_b32_e32 v126, v127
	v_mov_b32_e32 v125, v127
	v_mov_b32_e32 v124, v127
	v_mov_b32_e32 v123, v127
	v_mov_b32_e32 v122, v127
	v_mov_b32_e32 v121, v127
	v_mov_b32_e32 v120, v127
	v_mov_b32_e32 v111, v127
	v_mov_b32_e32 v110, v127
	v_mov_b32_e32 v109, v127
	v_mov_b32_e32 v108, v127
	v_mov_b32_e32 v107, v127
	v_mov_b32_e32 v106, v127
	v_mov_b32_e32 v105, v127
	v_mov_b32_e32 v104, v127
	v_mov_b32_e32 v95, v127
	v_mov_b32_e32 v94, v127
	v_mov_b32_e32 v93, v127
	v_mov_b32_e32 v92, v127
	v_mov_b32_e32 v91, v127
	v_mov_b32_e32 v90, v127
	v_mov_b32_e32 v89, v127
	v_mov_b32_e32 v88, v127
	v_mov_b32_e32 v79, v127
	v_mov_b32_e32 v78, v127
	v_mov_b32_e32 v77, v127
	v_mov_b32_e32 v76, v127
	v_mov_b32_e32 v75, v127
	v_mov_b32_e32 v74, v127
	v_mov_b32_e32 v73, v127
	v_mov_b32_e32 v72, v127
	v_mov_b32_e32 v119, v127
	v_mov_b32_e32 v118, v127
	v_mov_b32_e32 v117, v127
	v_mov_b32_e32 v116, v127
	v_mov_b32_e32 v115, v127
	v_mov_b32_e32 v114, v127
	v_mov_b32_e32 v113, v127
	v_mov_b32_e32 v112, v127
	v_mov_b32_e32 v103, v127
	v_mov_b32_e32 v102, v127
	v_mov_b32_e32 v101, v127
	v_mov_b32_e32 v100, v127
	v_mov_b32_e32 v99, v127
	v_mov_b32_e32 v98, v127
	v_mov_b32_e32 v97, v127
	v_mov_b32_e32 v96, v127
	v_mov_b32_e32 v87, v127
	v_mov_b32_e32 v86, v127
	v_mov_b32_e32 v85, v127
	v_mov_b32_e32 v84, v127
	v_mov_b32_e32 v83, v127
	v_mov_b32_e32 v82, v127
	v_mov_b32_e32 v81, v127
	v_mov_b32_e32 v80, v127
	v_mov_b32_e32 v71, v127
	v_mov_b32_e32 v70, v127
	v_mov_b32_e32 v69, v127
	v_mov_b32_e32 v68, v127
	v_mov_b32_e32 v67, v127
	v_mov_b32_e32 v66, v127
	v_mov_b32_e32 v65, v127
	v_mov_b32_e32 v64, v127
	v_mov_b32_e32 v63, v127
	v_mov_b32_e32 v62, v127
	v_mov_b32_e32 v61, v127
	v_mov_b32_e32 v60, v127
	v_mov_b32_e32 v59, v127
	v_mov_b32_e32 v58, v127
	v_mov_b32_e32 v57, v127
	v_mov_b32_e32 v56, v127
	v_mov_b32_e32 v47, v127
	v_mov_b32_e32 v46, v127
	v_mov_b32_e32 v45, v127
	v_mov_b32_e32 v44, v127
	v_mov_b32_e32 v43, v127
	v_mov_b32_e32 v42, v127
	v_mov_b32_e32 v41, v127
	v_mov_b32_e32 v40, v127
	v_mov_b32_e32 v31, v127
	v_mov_b32_e32 v30, v127
	v_mov_b32_e32 v29, v127
	v_mov_b32_e32 v28, v127
	v_mov_b32_e32 v27, v127
	v_mov_b32_e32 v26, v127
	v_mov_b32_e32 v25, v127
	v_mov_b32_e32 v24, v127
	v_mov_b32_e32 v15, v127
	v_mov_b32_e32 v14, v127
	v_mov_b32_e32 v13, v127
	v_mov_b32_e32 v12, v127
	v_mov_b32_e32 v11, v127
	v_mov_b32_e32 v10, v127
	v_mov_b32_e32 v9, v127
	v_mov_b32_e32 v8, v127
	v_mov_b32_e32 v55, v127
	v_mov_b32_e32 v54, v127
	v_mov_b32_e32 v53, v127
	v_mov_b32_e32 v52, v127
	v_mov_b32_e32 v51, v127
	v_mov_b32_e32 v50, v127
	v_mov_b32_e32 v49, v127
	v_mov_b32_e32 v48, v127
	v_mov_b32_e32 v39, v127
	v_mov_b32_e32 v38, v127
	v_mov_b32_e32 v37, v127
	v_mov_b32_e32 v36, v127
	v_mov_b32_e32 v35, v127
	v_mov_b32_e32 v34, v127
	v_mov_b32_e32 v33, v127
	v_mov_b32_e32 v32, v127
	v_mov_b32_e32 v23, v127
	v_mov_b32_e32 v22, v127
	v_mov_b32_e32 v21, v127
	v_mov_b32_e32 v20, v127
	v_mov_b32_e32 v19, v127
	v_mov_b32_e32 v18, v127
	v_mov_b32_e32 v17, v127
	v_mov_b32_e32 v16, v127
	v_mov_b32_e32 v7, v127
	v_mov_b32_e32 v6, v127
	v_mov_b32_e32 v5, v127
	v_mov_b32_e32 v4, v127
	v_mov_b32_e32 v3, v127
	v_mov_b32_e32 v2, v127
	v_mov_b32_e32 v1, v127
	v_mov_b32_e32 v0, v127
	s_cbranch_vccnz .LBB0_713
	s_add_u32 s83, s54, 0x100
	s_addc_u32 s84, s55, 0
	s_add_u32 s54, s56, 0x80
	v_mov_b32_e32 v0, 0
	s_addc_u32 s55, s57, 0
	s_mov_b32 s56, 0
	v_mov_b32_e32 v1, v0
	v_mov_b32_e32 v2, v0
	v_mov_b32_e32 v3, v0
	v_mov_b32_e32 v4, v0
	v_mov_b32_e32 v5, v0
	v_mov_b32_e32 v6, v0
	v_mov_b32_e32 v7, v0
	v_mov_b32_e32 v16, v0
	v_mov_b32_e32 v17, v0
	v_mov_b32_e32 v18, v0
	v_mov_b32_e32 v19, v0
	v_mov_b32_e32 v20, v0
	v_mov_b32_e32 v21, v0
	v_mov_b32_e32 v22, v0
	v_mov_b32_e32 v23, v0
	v_mov_b32_e32 v32, v0
	v_mov_b32_e32 v33, v0
	v_mov_b32_e32 v34, v0
	v_mov_b32_e32 v35, v0
	v_mov_b32_e32 v36, v0
	v_mov_b32_e32 v37, v0
	v_mov_b32_e32 v38, v0
	v_mov_b32_e32 v39, v0
	v_mov_b32_e32 v48, v0
	v_mov_b32_e32 v49, v0
	v_mov_b32_e32 v50, v0
	v_mov_b32_e32 v51, v0
	v_mov_b32_e32 v52, v0
	v_mov_b32_e32 v53, v0
	v_mov_b32_e32 v54, v0
	v_mov_b32_e32 v55, v0
	v_mov_b32_e32 v8, v0
	v_mov_b32_e32 v9, v0
	v_mov_b32_e32 v10, v0
	v_mov_b32_e32 v11, v0
	v_mov_b32_e32 v12, v0
	v_mov_b32_e32 v13, v0
	v_mov_b32_e32 v14, v0
	v_mov_b32_e32 v15, v0
	v_mov_b32_e32 v24, v0
	v_mov_b32_e32 v25, v0
	v_mov_b32_e32 v26, v0
	v_mov_b32_e32 v27, v0
	v_mov_b32_e32 v28, v0
	v_mov_b32_e32 v29, v0
	v_mov_b32_e32 v30, v0
	v_mov_b32_e32 v31, v0
	v_mov_b32_e32 v40, v0
	v_mov_b32_e32 v41, v0
	v_mov_b32_e32 v42, v0
	v_mov_b32_e32 v43, v0
	v_mov_b32_e32 v44, v0
	v_mov_b32_e32 v45, v0
	v_mov_b32_e32 v46, v0
	v_mov_b32_e32 v47, v0
	v_mov_b32_e32 v56, v0
	v_mov_b32_e32 v57, v0
	v_mov_b32_e32 v58, v0
	v_mov_b32_e32 v59, v0
	v_mov_b32_e32 v60, v0
	v_mov_b32_e32 v61, v0
	v_mov_b32_e32 v62, v0
	v_mov_b32_e32 v63, v0
	v_mov_b32_e32 v64, v0
	v_mov_b32_e32 v65, v0
	v_mov_b32_e32 v66, v0
	v_mov_b32_e32 v67, v0
	v_mov_b32_e32 v68, v0
	v_mov_b32_e32 v69, v0
	v_mov_b32_e32 v70, v0
	v_mov_b32_e32 v71, v0
	v_mov_b32_e32 v80, v0
	v_mov_b32_e32 v81, v0
	v_mov_b32_e32 v82, v0
	v_mov_b32_e32 v83, v0
	v_mov_b32_e32 v84, v0
	v_mov_b32_e32 v85, v0
	v_mov_b32_e32 v86, v0
	v_mov_b32_e32 v87, v0
	v_mov_b32_e32 v96, v0
	v_mov_b32_e32 v97, v0
	v_mov_b32_e32 v98, v0
	v_mov_b32_e32 v99, v0
	v_mov_b32_e32 v100, v0
	v_mov_b32_e32 v101, v0
	v_mov_b32_e32 v102, v0
	v_mov_b32_e32 v103, v0
	v_mov_b32_e32 v112, v0
	v_mov_b32_e32 v113, v0
	v_mov_b32_e32 v114, v0
	v_mov_b32_e32 v115, v0
	v_mov_b32_e32 v116, v0
	v_mov_b32_e32 v117, v0
	v_mov_b32_e32 v118, v0
	v_mov_b32_e32 v119, v0
	v_mov_b32_e32 v72, v0
	v_mov_b32_e32 v73, v0
	v_mov_b32_e32 v74, v0
	v_mov_b32_e32 v75, v0
	v_mov_b32_e32 v76, v0
	v_mov_b32_e32 v77, v0
	v_mov_b32_e32 v78, v0
	v_mov_b32_e32 v79, v0
	v_mov_b32_e32 v88, v0
	v_mov_b32_e32 v89, v0
	v_mov_b32_e32 v90, v0
	v_mov_b32_e32 v91, v0
	v_mov_b32_e32 v92, v0
	v_mov_b32_e32 v93, v0
	v_mov_b32_e32 v94, v0
	v_mov_b32_e32 v95, v0
	v_mov_b32_e32 v104, v0
	v_mov_b32_e32 v105, v0
	v_mov_b32_e32 v106, v0
	v_mov_b32_e32 v107, v0
	v_mov_b32_e32 v108, v0
	v_mov_b32_e32 v109, v0
	v_mov_b32_e32 v110, v0
	v_mov_b32_e32 v111, v0
	v_mov_b32_e32 v120, v0
	v_mov_b32_e32 v121, v0
	v_mov_b32_e32 v122, v0
	v_mov_b32_e32 v123, v0
	v_mov_b32_e32 v124, v0
	v_mov_b32_e32 v125, v0
	v_mov_b32_e32 v126, v0
	v_mov_b32_e32 v127, v0
	.p2align 6

; template <class Epi, class Sched, bool ALIGN_EPI = false, bool SP2 = false>
; __device__ __forceinline__ void gemm_phase(PG8_LAS unsigned char* lds, const Gemm g, const Sched& S, const Epi& E) {
;     ...
;     for (;;) {
;         const bool has_next = S.next(ui + 1, nxt);
;         const char* nA = has_next ? (const char*)g.A + (size_t)nxt.pm * tstep : cA; const char* nB = has_next ? (const char*)g.Bt + (size_t)nxt.pn * tstep : cB;
;         for (int t = 0; t < nt; t += 2) {
;             const bool last = (t == nt - 2);
;             const char* a1 = cA + (size_t)(t + 1) * kstep;
;             const char* a2 = last ? nA : cA + (size_t)(t + 2) * kstep; const char* b2 = last ? nB : cB + (size_t)(t + 2) * kstep;
;             const char* a3 = a2 + kstep; const char* b3 = b2 + kstep;
;     ...
; #pragma unroll
;         for (int a = 0; a < 2; ++a)
; #pragma unroll
;             for (int b = 0; b < 2; ++b)
; #pragma unroll
;                 for (int m = 0; m < 4; ++m)
; #pragma unroll
;                     for (int n = 0; n < 2; ++n) acc[a][b][m][n] = (f32x4){0.f, 0.f, 0.f, 0.f};
;         cur = nxt; cA = nA; cB = nB; ++ui;
.LBB0_739:
	v_mov_b32_e32 v127, 0
	s_andn2_b64 vcc, exec, s[36:37]
	v_mov_b32_e32 v126, 0
	v_mov_b32_e32 v125, 0
	v_mov_b32_e32 v124, 0
	v_mov_b32_e32 v123, 0
	v_mov_b32_e32 v122, 0
	v_mov_b32_e32 v121, 0
	v_mov_b32_e32 v120, 0
	v_mov_b32_e32 v101, 0
	v_mov_b32_e32 v100, 0
	v_mov_b32_e32 v103, 0
	v_mov_b32_e32 v102, 0
	v_mov_b32_e32 v109, 0
	v_mov_b32_e32 v108, 0
	v_mov_b32_e32 v111, 0
	v_mov_b32_e32 v110, 0
	v_mov_b32_e32 v85, 0
	v_mov_b32_e32 v84, 0
	v_mov_b32_e32 v87, 0
	v_mov_b32_e32 v86, 0
	v_mov_b32_e32 v93, 0
	v_mov_b32_e32 v92, 0
	v_mov_b32_e32 v95, 0
	v_mov_b32_e32 v94, 0
	v_mov_b32_e32 v73, 0
	v_mov_b32_e32 v72, 0
	v_mov_b32_e32 v75, 0
	v_mov_b32_e32 v74, 0
	v_mov_b32_e32 v77, 0
	v_mov_b32_e32 v76, 0
	v_mov_b32_e32 v79, 0
	v_mov_b32_e32 v78, 0
	v_mov_b32_e32 v153, 0
	v_mov_b32_e32 v152, 0
	v_mov_b32_e32 v155, 0
	v_mov_b32_e32 v154, 0
	v_mov_b32_e32 v157, 0
	v_mov_b32_e32 v156, 0
	v_mov_b32_e32 v159, 0
	v_mov_b32_e32 v158, 0
	v_mov_b32_e32 v113, 0
	v_mov_b32_e32 v112, 0
	v_mov_b32_e32 v115, 0
	v_mov_b32_e32 v114, 0
	v_mov_b32_e32 v117, 0
	v_mov_b32_e32 v116, 0
	v_mov_b32_e32 v119, 0
	v_mov_b32_e32 v118, 0
	v_mov_b32_e32 v97, 0
	v_mov_b32_e32 v96, 0
	v_mov_b32_e32 v99, 0
	v_mov_b32_e32 v98, 0
	v_mov_b32_e32 v105, 0
	v_mov_b32_e32 v104, 0
	v_mov_b32_e32 v107, 0
	v_mov_b32_e32 v106, 0
	v_mov_b32_e32 v71, 0
	v_mov_b32_e32 v70, 0
	v_mov_b32_e32 v69, 0
	v_mov_b32_e32 v68, 0
	v_mov_b32_e32 v67, 0
	v_mov_b32_e32 v66, 0
	v_mov_b32_e32 v65, 0
	v_mov_b32_e32 v64, 0
	v_mov_b32_e32 v63, 0
	v_mov_b32_e32 v62, 0
	v_mov_b32_e32 v61, 0
	v_mov_b32_e32 v60, 0
	v_mov_b32_e32 v59, 0
	v_mov_b32_e32 v58, 0
	v_mov_b32_e32 v57, 0
	v_mov_b32_e32 v56, 0
	v_mov_b32_e32 v37, 0
	v_mov_b32_e32 v36, 0
	v_mov_b32_e32 v39, 0
	v_mov_b32_e32 v38, 0
	v_mov_b32_e32 v45, 0
	v_mov_b32_e32 v44, 0
	v_mov_b32_e32 v47, 0
	v_mov_b32_e32 v46, 0
	v_mov_b32_e32 v21, 0
	v_mov_b32_e32 v20, 0
	v_mov_b32_e32 v23, 0
	v_mov_b32_e32 v22, 0
	v_mov_b32_e32 v29, 0
	v_mov_b32_e32 v28, 0
	v_mov_b32_e32 v31, 0
	v_mov_b32_e32 v30, 0
	v_mov_b32_e32 v9, 0
	v_mov_b32_e32 v8, 0
	v_mov_b32_e32 v11, 0
	v_mov_b32_e32 v10, 0
	v_mov_b32_e32 v13, 0
	v_mov_b32_e32 v12, 0
	v_mov_b32_e32 v15, 0
	v_mov_b32_e32 v14, 0
	v_mov_b32_e32 v81, 0
	v_mov_b32_e32 v80, 0
	v_mov_b32_e32 v83, 0
	v_mov_b32_e32 v82, 0
	v_mov_b32_e32 v89, 0
	v_mov_b32_e32 v88, 0
	v_mov_b32_e32 v91, 0
	v_mov_b32_e32 v90, 0
	v_mov_b32_e32 v49, 0
	v_mov_b32_e32 v48, 0
	v_mov_b32_e32 v51, 0
	v_mov_b32_e32 v50, 0
	v_mov_b32_e32 v53, 0
	v_mov_b32_e32 v52, 0
	v_mov_b32_e32 v55, 0
	v_mov_b32_e32 v54, 0
	v_mov_b32_e32 v33, 0
	v_mov_b32_e32 v32, 0
	v_mov_b32_e32 v35, 0
	v_mov_b32_e32 v34, 0
	v_mov_b32_e32 v41, 0
	v_mov_b32_e32 v40, 0
	v_mov_b32_e32 v43, 0
	v_mov_b32_e32 v42, 0
	v_mov_b32_e32 v7, 0
	v_mov_b32_e32 v6, 0
	v_mov_b32_e32 v5, 0
	v_mov_b32_e32 v4, 0
	v_mov_b32_e32 v3, 0
	v_mov_b32_e32 v2, 0
	v_mov_b32_e32 v1, 0
	v_mov_b32_e32 v0, 0
	s_cbranch_vccnz .LBB0_743
	s_add_u32 s78, s50, 0x100
	s_addc_u32 s79, s51, 0
	s_add_u32 s50, s52, 0x80
	v_mov_b32_e32 v0, 0
	s_addc_u32 s51, s53, 0
	s_mov_b32 s52, 0
	v_mov_b32_e32 v1, v0
	v_mov_b32_e32 v2, v0
	v_mov_b32_e32 v3, v0
	v_mov_b32_e32 v4, v0
	v_mov_b32_e32 v5, v0
	v_mov_b32_e32 v6, v0
	v_mov_b32_e32 v7, v0
	v_mov_b32_e32 v8, v0
	v_mov_b32_e32 v9, v0
	v_mov_b32_e32 v10, v0
	v_mov_b32_e32 v11, v0
	v_mov_b32_e32 v12, v0
	v_mov_b32_e32 v13, v0
	v_mov_b32_e32 v14, v0
	v_mov_b32_e32 v15, v0
	v_mov_b32_e32 v20, v0
	v_mov_b32_e32 v21, v0
	v_mov_b32_e32 v22, v0
	v_mov_b32_e32 v23, v0
	v_mov_b32_e32 v28, v0
	v_mov_b32_e32 v29, v0
	v_mov_b32_e32 v30, v0
	v_mov_b32_e32 v31, v0
	v_mov_b32_e32 v36, v0
	v_mov_b32_e32 v37, v0
	v_mov_b32_e32 v38, v0
	v_mov_b32_e32 v39, v0
	v_mov_b32_e32 v44, v0
	v_mov_b32_e32 v45, v0
	v_mov_b32_e32 v46, v0
	v_mov_b32_e32 v47, v0
	v_mov_b32_e32 v16, v0
	v_mov_b32_e32 v17, v0
	v_mov_b32_e32 v18, v0
	v_mov_b32_e32 v19, v0
	v_mov_b32_e32 v24, v0
	v_mov_b32_e32 v25, v0
	v_mov_b32_e32 v26, v0
	v_mov_b32_e32 v27, v0
	v_mov_b32_e32 v32, v0
	v_mov_b32_e32 v33, v0
	v_mov_b32_e32 v34, v0
	v_mov_b32_e32 v35, v0
	v_mov_b32_e32 v40, v0
	v_mov_b32_e32 v41, v0
	v_mov_b32_e32 v42, v0
	v_mov_b32_e32 v43, v0
	v_mov_b32_e32 v48, v0
	v_mov_b32_e32 v49, v0
	v_mov_b32_e32 v50, v0
	v_mov_b32_e32 v51, v0
	v_mov_b32_e32 v52, v0
	v_mov_b32_e32 v53, v0
	v_mov_b32_e32 v54, v0
	v_mov_b32_e32 v55, v0
	v_mov_b32_e32 v56, v0
	v_mov_b32_e32 v57, v0
	v_mov_b32_e32 v58, v0
	v_mov_b32_e32 v59, v0
	v_mov_b32_e32 v60, v0
	v_mov_b32_e32 v61, v0
	v_mov_b32_e32 v62, v0
	v_mov_b32_e32 v63, v0
	v_mov_b32_e32 v64, v0
	v_mov_b32_e32 v65, v0
	v_mov_b32_e32 v66, v0
	v_mov_b32_e32 v67, v0
	v_mov_b32_e32 v68, v0
	v_mov_b32_e32 v69, v0
	v_mov_b32_e32 v70, v0
	v_mov_b32_e32 v71, v0
	v_mov_b32_e32 v72, v0
	v_mov_b32_e32 v73, v0
	v_mov_b32_e32 v74, v0
	v_mov_b32_e32 v75, v0
	v_mov_b32_e32 v76, v0
	v_mov_b32_e32 v77, v0
	v_mov_b32_e32 v78, v0
	v_mov_b32_e32 v79, v0
	v_mov_b32_e32 v84, v0
	v_mov_b32_e32 v85, v0
	v_mov_b32_e32 v86, v0
	v_mov_b32_e32 v87, v0
	v_mov_b32_e32 v92, v0
	v_mov_b32_e32 v93, v0
	v_mov_b32_e32 v94, v0
	v_mov_b32_e32 v95, v0
	v_mov_b32_e32 v100, v0
	v_mov_b32_e32 v101, v0
	v_mov_b32_e32 v102, v0
	v_mov_b32_e32 v103, v0
	v_mov_b32_e32 v108, v0
	v_mov_b32_e32 v109, v0
	v_mov_b32_e32 v110, v0
	v_mov_b32_e32 v111, v0
	v_mov_b32_e32 v80, v0
	v_mov_b32_e32 v81, v0
	v_mov_b32_e32 v82, v0
	v_mov_b32_e32 v83, v0
	v_mov_b32_e32 v88, v0
	v_mov_b32_e32 v89, v0
	v_mov_b32_e32 v90, v0
	v_mov_b32_e32 v91, v0
	v_mov_b32_e32 v96, v0
	v_mov_b32_e32 v97, v0
	v_mov_b32_e32 v98, v0
	v_mov_b32_e32 v99, v0
	v_mov_b32_e32 v104, v0
	v_mov_b32_e32 v105, v0
	v_mov_b32_e32 v106, v0
	v_mov_b32_e32 v107, v0
	v_mov_b32_e32 v112, v0
	v_mov_b32_e32 v113, v0
	v_mov_b32_e32 v114, v0
	v_mov_b32_e32 v115, v0
	v_mov_b32_e32 v116, v0
	v_mov_b32_e32 v117, v0
	v_mov_b32_e32 v118, v0
	v_mov_b32_e32 v119, v0
	v_mov_b32_e32 v120, v0
	v_mov_b32_e32 v121, v0
	v_mov_b32_e32 v122, v0
	v_mov_b32_e32 v123, v0
	v_mov_b32_e32 v124, v0
	v_mov_b32_e32 v125, v0
	v_mov_b32_e32 v126, v0
	v_mov_b32_e32 v127, v0
	.p2align 6

; template <class Epi, class Sched, bool ALIGN_EPI = false, bool SP2 = false>
; __device__ __forceinline__ void gemm_phase(PG8_LAS unsigned char* lds, const Gemm g, const Sched& S, const Epi& E) {
;     ...
;     for (;;) {
;         const bool has_next = S.next(ui + 1, nxt);
;         const char* nA = has_next ? (const char*)g.A + (size_t)nxt.pm * tstep : cA; const char* nB = has_next ? (const char*)g.Bt + (size_t)nxt.pn * tstep : cB;
;         for (int t = 0; t < nt; t += 2) {
;             const bool last = (t == nt - 2);
;             const char* a1 = cA + (size_t)(t + 1) * kstep;
;             const char* a2 = last ? nA : cA + (size_t)(t + 2) * kstep; const char* b2 = last ? nB : cB + (size_t)(t + 2) * kstep;
;             const char* a3 = a2 + kstep; const char* b3 = b2 + kstep;
.LBB0_1294:
	s_add_u32 s68, s30, 0x100
	s_addc_u32 s69, s31, 0
	s_add_u32 s42, s34, 0x80
	s_addc_u32 s43, s35, 0
	s_mov_b32 s44, 0
	.p2align 6

; template <class Epi, class Sched, bool ALIGN_EPI = false, bool SP2 = false>
; __device__ __forceinline__ void gemm_phase(PG8_LAS unsigned char* lds, const Gemm g, const Sched& S, const Epi& E) {
;     ...
;     for (;;) {
;         const bool has_next = S.next(ui + 1, nxt);
;         const char* nA = has_next ? (const char*)g.A + (size_t)nxt.pm * tstep : cA; const char* nB = has_next ? (const char*)g.Bt + (size_t)nxt.pn * tstep : cB;
;         for (int t = 0; t < nt; t += 2) {
;             const bool last = (t == nt - 2);
;             const char* a1 = cA + (size_t)(t + 1) * kstep;
;             const char* a2 = last ? nA : cA + (size_t)(t + 2) * kstep; const char* b2 = last ? nB : cB + (size_t)(t + 2) * kstep;
;             const char* a3 = a2 + kstep; const char* b3 = b2 + kstep;
;     ...
; #pragma unroll
;         for (int a = 0; a < 2; ++a)
; #pragma unroll
;             for (int b = 0; b < 2; ++b)
; #pragma unroll
;                 for (int m = 0; m < 4; ++m)
; #pragma unroll
;                     for (int n = 0; n < 2; ++n) acc[a][b][m][n] = (f32x4){0.f, 0.f, 0.f, 0.f};
;         cur = nxt; cA = nA; cB = nB; ++ui;
.LBB0_1404:
	v_mov_b32_e32 v127, 0
	s_andn2_b64 vcc, exec, s[20:21]
	v_mov_b32_e32 v126, v127
	v_mov_b32_e32 v125, v127
	v_mov_b32_e32 v124, v127
	v_mov_b32_e32 v119, v127
	v_mov_b32_e32 v118, v127
	v_mov_b32_e32 v117, v127
	v_mov_b32_e32 v116, v127
	v_mov_b32_e32 v111, v127
	v_mov_b32_e32 v110, v127
	v_mov_b32_e32 v109, v127
	v_mov_b32_e32 v108, v127
	v_mov_b32_e32 v103, v127
	v_mov_b32_e32 v102, v127
	v_mov_b32_e32 v101, v127
	v_mov_b32_e32 v100, v127
	v_mov_b32_e32 v95, v127
	v_mov_b32_e32 v94, v127
	v_mov_b32_e32 v93, v127
	v_mov_b32_e32 v92, v127
	v_mov_b32_e32 v87, v127
	v_mov_b32_e32 v86, v127
	v_mov_b32_e32 v85, v127
	v_mov_b32_e32 v84, v127
	v_mov_b32_e32 v79, v127
	v_mov_b32_e32 v78, v127
	v_mov_b32_e32 v77, v127
	v_mov_b32_e32 v76, v127
	v_mov_b32_e32 v71, v127
	v_mov_b32_e32 v70, v127
	v_mov_b32_e32 v69, v127
	v_mov_b32_e32 v68, v127
	v_mov_b32_e32 v123, v127
	v_mov_b32_e32 v122, v127
	v_mov_b32_e32 v121, v127
	v_mov_b32_e32 v120, v127
	v_mov_b32_e32 v115, v127
	v_mov_b32_e32 v114, v127
	v_mov_b32_e32 v113, v127
	v_mov_b32_e32 v112, v127
	v_mov_b32_e32 v107, v127
	v_mov_b32_e32 v106, v127
	v_mov_b32_e32 v105, v127
	v_mov_b32_e32 v104, v127
	v_mov_b32_e32 v99, v127
	v_mov_b32_e32 v98, v127
	v_mov_b32_e32 v97, v127
	v_mov_b32_e32 v96, v127
	v_mov_b32_e32 v91, v127
	v_mov_b32_e32 v90, v127
	v_mov_b32_e32 v89, v127
	v_mov_b32_e32 v88, v127
	v_mov_b32_e32 v83, v127
	v_mov_b32_e32 v82, v127
	v_mov_b32_e32 v81, v127
	v_mov_b32_e32 v80, v127
	v_mov_b32_e32 v75, v127
	v_mov_b32_e32 v74, v127
	v_mov_b32_e32 v73, v127
	v_mov_b32_e32 v72, v127
	v_mov_b32_e32 v67, v127
	v_mov_b32_e32 v66, v127
	v_mov_b32_e32 v65, v127
	v_mov_b32_e32 v64, v127
	v_mov_b32_e32 v63, v127
	v_mov_b32_e32 v62, v127
	v_mov_b32_e32 v61, v127
	v_mov_b32_e32 v60, v127
	v_mov_b32_e32 v55, v127
	v_mov_b32_e32 v54, v127
	v_mov_b32_e32 v53, v127
	v_mov_b32_e32 v52, v127
	v_mov_b32_e32 v47, v127
	v_mov_b32_e32 v46, v127
	v_mov_b32_e32 v45, v127
	v_mov_b32_e32 v44, v127
	v_mov_b32_e32 v39, v127
	v_mov_b32_e32 v38, v127
	v_mov_b32_e32 v37, v127
	v_mov_b32_e32 v36, v127
	v_mov_b32_e32 v31, v127
	v_mov_b32_e32 v30, v127
	v_mov_b32_e32 v29, v127
	v_mov_b32_e32 v28, v127
	v_mov_b32_e32 v23, v127
	v_mov_b32_e32 v22, v127
	v_mov_b32_e32 v21, v127
	v_mov_b32_e32 v20, v127
	v_mov_b32_e32 v15, v127
	v_mov_b32_e32 v14, v127
	v_mov_b32_e32 v13, v127
	v_mov_b32_e32 v12, v127
	v_mov_b32_e32 v7, v127
	v_mov_b32_e32 v6, v127
	v_mov_b32_e32 v5, v127
	v_mov_b32_e32 v4, v127
	v_mov_b32_e32 v59, v127
	v_mov_b32_e32 v58, v127
	v_mov_b32_e32 v57, v127
	v_mov_b32_e32 v56, v127
	v_mov_b32_e32 v51, v127
	v_mov_b32_e32 v50, v127
	v_mov_b32_e32 v49, v127
	v_mov_b32_e32 v48, v127
	v_mov_b32_e32 v43, v127
	v_mov_b32_e32 v42, v127
	v_mov_b32_e32 v41, v127
	v_mov_b32_e32 v40, v127
	v_mov_b32_e32 v35, v127
	v_mov_b32_e32 v34, v127
	v_mov_b32_e32 v33, v127
	v_mov_b32_e32 v32, v127
	v_mov_b32_e32 v27, v127
	v_mov_b32_e32 v26, v127
	v_mov_b32_e32 v25, v127
	v_mov_b32_e32 v24, v127
	v_mov_b32_e32 v19, v127
	v_mov_b32_e32 v18, v127
	v_mov_b32_e32 v17, v127
	v_mov_b32_e32 v16, v127
	v_mov_b32_e32 v11, v127
	v_mov_b32_e32 v10, v127
	v_mov_b32_e32 v9, v127
	v_mov_b32_e32 v8, v127
	v_mov_b32_e32 v3, v127
	v_mov_b32_e32 v2, v127
	v_mov_b32_e32 v1, v127
	v_mov_b32_e32 v0, v127
	s_cbranch_vccnz .LBB0_1407
	s_add_u32 s64, s36, 0x100
	s_addc_u32 s65, s37, 0
	s_add_u32 s36, s38, 0x80
	v_mov_b32_e32 v0, 0
	s_addc_u32 s37, s39, 0
	s_mov_b32 s38, 0
	v_mov_b32_e32 v1, v0
	v_mov_b32_e32 v2, v0
	v_mov_b32_e32 v3, v0
	v_mov_b32_e32 v8, v0
	v_mov_b32_e32 v9, v0
	v_mov_b32_e32 v10, v0
	v_mov_b32_e32 v11, v0
	v_mov_b32_e32 v16, v0
	v_mov_b32_e32 v17, v0
	v_mov_b32_e32 v18, v0
	v_mov_b32_e32 v19, v0
	v_mov_b32_e32 v24, v0
	v_mov_b32_e32 v25, v0
	v_mov_b32_e32 v26, v0
	v_mov_b32_e32 v27, v0
	v_mov_b32_e32 v32, v0
	v_mov_b32_e32 v33, v0
	v_mov_b32_e32 v34, v0
	v_mov_b32_e32 v35, v0
	v_mov_b32_e32 v40, v0
	v_mov_b32_e32 v41, v0
	v_mov_b32_e32 v42, v0
	v_mov_b32_e32 v43, v0
	v_mov_b32_e32 v48, v0
	v_mov_b32_e32 v49, v0
	v_mov_b32_e32 v50, v0
	v_mov_b32_e32 v51, v0
	v_mov_b32_e32 v56, v0
	v_mov_b32_e32 v57, v0
	v_mov_b32_e32 v58, v0
	v_mov_b32_e32 v59, v0
	v_mov_b32_e32 v4, v0
	v_mov_b32_e32 v5, v0
	v_mov_b32_e32 v6, v0
	v_mov_b32_e32 v7, v0
	v_mov_b32_e32 v12, v0
	v_mov_b32_e32 v13, v0
	v_mov_b32_e32 v14, v0
	v_mov_b32_e32 v15, v0
	v_mov_b32_e32 v20, v0
	v_mov_b32_e32 v21, v0
	v_mov_b32_e32 v22, v0
	v_mov_b32_e32 v23, v0
	v_mov_b32_e32 v28, v0
	v_mov_b32_e32 v29, v0
	v_mov_b32_e32 v30, v0
	v_mov_b32_e32 v31, v0
	v_mov_b32_e32 v36, v0
	v_mov_b32_e32 v37, v0
	v_mov_b32_e32 v38, v0
	v_mov_b32_e32 v39, v0
	v_mov_b32_e32 v44, v0
	v_mov_b32_e32 v45, v0
	v_mov_b32_e32 v46, v0
	v_mov_b32_e32 v47, v0
	v_mov_b32_e32 v52, v0
	v_mov_b32_e32 v53, v0
	v_mov_b32_e32 v54, v0
	v_mov_b32_e32 v55, v0
	v_mov_b32_e32 v60, v0
	v_mov_b32_e32 v61, v0
	v_mov_b32_e32 v62, v0
	v_mov_b32_e32 v63, v0
	v_mov_b32_e32 v64, v0
	v_mov_b32_e32 v65, v0
	v_mov_b32_e32 v66, v0
	v_mov_b32_e32 v67, v0
	v_mov_b32_e32 v72, v0
	v_mov_b32_e32 v73, v0
	v_mov_b32_e32 v74, v0
	v_mov_b32_e32 v75, v0
	v_mov_b32_e32 v80, v0
	v_mov_b32_e32 v81, v0
	v_mov_b32_e32 v82, v0
	v_mov_b32_e32 v83, v0
	v_mov_b32_e32 v88, v0
	v_mov_b32_e32 v89, v0
	v_mov_b32_e32 v90, v0
	v_mov_b32_e32 v91, v0
	v_mov_b32_e32 v96, v0
	v_mov_b32_e32 v97, v0
	v_mov_b32_e32 v98, v0
	v_mov_b32_e32 v99, v0
	v_mov_b32_e32 v104, v0
	v_mov_b32_e32 v105, v0
	v_mov_b32_e32 v106, v0
	v_mov_b32_e32 v107, v0
	v_mov_b32_e32 v112, v0
	v_mov_b32_e32 v113, v0
	v_mov_b32_e32 v114, v0
	v_mov_b32_e32 v115, v0
	v_mov_b32_e32 v120, v0
	v_mov_b32_e32 v121, v0
	v_mov_b32_e32 v122, v0
	v_mov_b32_e32 v123, v0
	v_mov_b32_e32 v68, v0
	v_mov_b32_e32 v69, v0
	v_mov_b32_e32 v70, v0
	v_mov_b32_e32 v71, v0
	v_mov_b32_e32 v76, v0
	v_mov_b32_e32 v77, v0
	v_mov_b32_e32 v78, v0
	v_mov_b32_e32 v79, v0
	v_mov_b32_e32 v84, v0
	v_mov_b32_e32 v85, v0
	v_mov_b32_e32 v86, v0
	v_mov_b32_e32 v87, v0
	v_mov_b32_e32 v92, v0
	v_mov_b32_e32 v93, v0
	v_mov_b32_e32 v94, v0
	v_mov_b32_e32 v95, v0
	v_mov_b32_e32 v100, v0
	v_mov_b32_e32 v101, v0
	v_mov_b32_e32 v102, v0
	v_mov_b32_e32 v103, v0
	v_mov_b32_e32 v108, v0
	v_mov_b32_e32 v109, v0
	v_mov_b32_e32 v110, v0
	v_mov_b32_e32 v111, v0
	v_mov_b32_e32 v116, v0
	v_mov_b32_e32 v117, v0
	v_mov_b32_e32 v118, v0
	v_mov_b32_e32 v119, v0
	v_mov_b32_e32 v124, v0
	v_mov_b32_e32 v125, v0
	v_mov_b32_e32 v126, v0
	v_mov_b32_e32 v127, v0
	.p2align 6

; template <class Epi, class Sched, bool ALIGN_EPI = false, bool SP2 = false>
; __device__ __forceinline__ void gemm_phase(PG8_LAS unsigned char* lds, const Gemm g, const Sched& S, const Epi& E) {
;     ...
;     for (;;) {
;         const bool has_next = S.next(ui + 1, nxt);
;         const char* nA = has_next ? (const char*)g.A + (size_t)nxt.pm * tstep : cA; const char* nB = has_next ? (const char*)g.Bt + (size_t)nxt.pn * tstep : cB;
;         for (int t = 0; t < nt; t += 2) {
;             const bool last = (t == nt - 2);
;             const char* a1 = cA + (size_t)(t + 1) * kstep;
;             const char* a2 = last ? nA : cA + (size_t)(t + 2) * kstep; const char* b2 = last ? nB : cB + (size_t)(t + 2) * kstep;
;             const char* a3 = a2 + kstep; const char* b3 = b2 + kstep;
.LBB0_1485:
	s_add_u32 s64, s16, 0x100
	s_addc_u32 s65, s17, 0
	s_add_u32 s36, s18, 0x80
	s_addc_u32 s37, s19, 0
	s_mov_b32 s38, 0
	.p2align 6
